# P0 adaLN: silu(c) staging loop rewritten straight-line with 32 loads in flight instead of 16 serial dependent-load iterations
# speedup vs baseline: 1.0022x; 1.0022x over previous
.LBB0_104:
	v_lshlrev_b32_e32 v13, 2, v62
	v_lshlrev_b32_e32 v15, 6, v62
	v_add_u32_e32 v16, 0x10000, v15
	v_add_u32_e32 v52, 0x0, v13
	v_add_u32_e32 v53, 0x1000, v13
	v_add_u32_e32 v54, 0x2000, v13
	v_add_u32_e32 v55, 0x3000, v13
	v_add_u32_e32 v56, 0x4000, v13
	v_add_u32_e32 v57, 0x5000, v13
	v_add_u32_e32 v58, 0x6000, v13
	v_add_u32_e32 v59, 0x7000, v13
	global_load_dword v20, v52, s[6:7]
	global_load_dword v21, v54, s[6:7]
	global_load_dword v22, v56, s[6:7]
	global_load_dword v23, v58, s[6:7]
	global_load_dword v24, v52, s[6:7] offset:2048
	global_load_dword v25, v54, s[6:7] offset:2048
	global_load_dword v26, v56, s[6:7] offset:2048
	global_load_dword v27, v58, s[6:7] offset:2048
	global_load_dword v28, v53, s[6:7]
	global_load_dword v29, v55, s[6:7]
	global_load_dword v30, v57, s[6:7]
	global_load_dword v31, v59, s[6:7]
	global_load_dword v32, v53, s[6:7] offset:2048
	global_load_dword v33, v55, s[6:7] offset:2048
	global_load_dword v34, v57, s[6:7] offset:2048
	global_load_dword v35, v59, s[6:7] offset:2048
	v_add_u32_e32 v52, 0x8000, v13
	v_add_u32_e32 v53, 0x9000, v13
	v_add_u32_e32 v54, 0xa000, v13
	v_add_u32_e32 v55, 0xb000, v13
	v_add_u32_e32 v56, 0xc000, v13
	v_add_u32_e32 v57, 0xd000, v13
	v_add_u32_e32 v58, 0xe000, v13
	v_add_u32_e32 v59, 0xf000, v13
	global_load_dword v36, v52, s[6:7]
	global_load_dword v37, v54, s[6:7]
	global_load_dword v38, v56, s[6:7]
	global_load_dword v39, v58, s[6:7]
	global_load_dword v40, v52, s[6:7] offset:2048
	global_load_dword v41, v54, s[6:7] offset:2048
	global_load_dword v42, v56, s[6:7] offset:2048
	global_load_dword v43, v58, s[6:7] offset:2048
	global_load_dword v44, v53, s[6:7]
	global_load_dword v45, v55, s[6:7]
	global_load_dword v46, v57, s[6:7]
	global_load_dword v47, v59, s[6:7]
	global_load_dword v48, v53, s[6:7] offset:2048
	global_load_dword v49, v55, s[6:7] offset:2048
	global_load_dword v50, v57, s[6:7] offset:2048
	global_load_dword v51, v59, s[6:7] offset:2048
	s_waitcnt vmcnt(16)
	v_mul_f32_e32 v74, 0xbfb8aa3b, v20
	v_mul_f32_e32 v75, 0xbfb8aa3b, v21
	v_mul_f32_e32 v76, 0xbfb8aa3b, v22
	v_mul_f32_e32 v77, 0xbfb8aa3b, v23
	v_exp_f32_e32 v74, v74
	v_exp_f32_e32 v75, v75
	v_exp_f32_e32 v76, v76
	v_exp_f32_e32 v77, v77
	v_add_f32_e32 v74, 1.0, v74
	v_add_f32_e32 v75, 1.0, v75
	v_add_f32_e32 v76, 1.0, v76
	v_add_f32_e32 v77, 1.0, v77
	v_rcp_f32_e32 v74, v74
	v_rcp_f32_e32 v75, v75
	v_rcp_f32_e32 v76, v76
	v_rcp_f32_e32 v77, v77
	v_mul_f32_e32 v74, v20, v74
	v_mul_f32_e32 v75, v21, v75
	v_mul_f32_e32 v76, v22, v76
	v_mul_f32_e32 v77, v23, v77
	ds_write_b128 v15, v[74:77]
	v_mul_f32_e32 v74, 0xbfb8aa3b, v24
	v_mul_f32_e32 v75, 0xbfb8aa3b, v25
	v_mul_f32_e32 v76, 0xbfb8aa3b, v26
	v_mul_f32_e32 v77, 0xbfb8aa3b, v27
	v_exp_f32_e32 v74, v74
	v_exp_f32_e32 v75, v75
	v_exp_f32_e32 v76, v76
	v_exp_f32_e32 v77, v77
	v_add_f32_e32 v74, 1.0, v74
	v_add_f32_e32 v75, 1.0, v75
	v_add_f32_e32 v76, 1.0, v76
	v_add_f32_e32 v77, 1.0, v77
	v_rcp_f32_e32 v74, v74
	v_rcp_f32_e32 v75, v75
	v_rcp_f32_e32 v76, v76
	v_rcp_f32_e32 v77, v77
	v_mul_f32_e32 v74, v24, v74
	v_mul_f32_e32 v75, v25, v75
	v_mul_f32_e32 v76, v26, v76
	v_mul_f32_e32 v77, v27, v77
	ds_write_b128 v15, v[74:77] offset:32768
	v_mul_f32_e32 v74, 0xbfb8aa3b, v28
	v_mul_f32_e32 v75, 0xbfb8aa3b, v29
	v_mul_f32_e32 v76, 0xbfb8aa3b, v30
	v_mul_f32_e32 v77, 0xbfb8aa3b, v31
	v_exp_f32_e32 v74, v74
	v_exp_f32_e32 v75, v75
	v_exp_f32_e32 v76, v76
	v_exp_f32_e32 v77, v77
	v_add_f32_e32 v74, 1.0, v74
	v_add_f32_e32 v75, 1.0, v75
	v_add_f32_e32 v76, 1.0, v76
	v_add_f32_e32 v77, 1.0, v77
	v_rcp_f32_e32 v74, v74
	v_rcp_f32_e32 v75, v75
	v_rcp_f32_e32 v76, v76
	v_rcp_f32_e32 v77, v77
	v_mul_f32_e32 v74, v28, v74
	v_mul_f32_e32 v75, v29, v75
	v_mul_f32_e32 v76, v30, v76
	v_mul_f32_e32 v77, v31, v77
	ds_write_b128 v16, v[74:77]
	v_mul_f32_e32 v74, 0xbfb8aa3b, v32
	v_mul_f32_e32 v75, 0xbfb8aa3b, v33
	v_mul_f32_e32 v76, 0xbfb8aa3b, v34
	v_mul_f32_e32 v77, 0xbfb8aa3b, v35
	v_exp_f32_e32 v74, v74
	v_exp_f32_e32 v75, v75
	v_exp_f32_e32 v76, v76
	v_exp_f32_e32 v77, v77
	v_add_f32_e32 v74, 1.0, v74
	v_add_f32_e32 v75, 1.0, v75
	v_add_f32_e32 v76, 1.0, v76
	v_add_f32_e32 v77, 1.0, v77
	v_rcp_f32_e32 v74, v74
	v_rcp_f32_e32 v75, v75
	v_rcp_f32_e32 v76, v76
	v_rcp_f32_e32 v77, v77
	v_mul_f32_e32 v74, v32, v74
	v_mul_f32_e32 v75, v33, v75
	v_mul_f32_e32 v76, v34, v76
	v_mul_f32_e32 v77, v35, v77
	ds_write_b128 v16, v[74:77] offset:32768
	v_add_u32_e32 v52, 0x10000, v13
	v_add_u32_e32 v53, 0x11000, v13
	v_add_u32_e32 v54, 0x12000, v13
	v_add_u32_e32 v55, 0x13000, v13
	v_add_u32_e32 v56, 0x14000, v13
	v_add_u32_e32 v57, 0x15000, v13
	v_add_u32_e32 v58, 0x16000, v13
	v_add_u32_e32 v59, 0x17000, v13
	global_load_dword v20, v52, s[6:7]
	global_load_dword v21, v54, s[6:7]
	global_load_dword v22, v56, s[6:7]
	global_load_dword v23, v58, s[6:7]
	global_load_dword v24, v52, s[6:7] offset:2048
	global_load_dword v25, v54, s[6:7] offset:2048
	global_load_dword v26, v56, s[6:7] offset:2048
	global_load_dword v27, v58, s[6:7] offset:2048
	global_load_dword v28, v53, s[6:7]
	global_load_dword v29, v55, s[6:7]
	global_load_dword v30, v57, s[6:7]
	global_load_dword v31, v59, s[6:7]
	global_load_dword v32, v53, s[6:7] offset:2048
	global_load_dword v33, v55, s[6:7] offset:2048
	global_load_dword v34, v57, s[6:7] offset:2048
	global_load_dword v35, v59, s[6:7] offset:2048
	s_waitcnt vmcnt(16)
	v_mul_f32_e32 v74, 0xbfb8aa3b, v36
	v_mul_f32_e32 v75, 0xbfb8aa3b, v37
	v_mul_f32_e32 v76, 0xbfb8aa3b, v38
	v_mul_f32_e32 v77, 0xbfb8aa3b, v39
	v_exp_f32_e32 v74, v74
	v_exp_f32_e32 v75, v75
	v_exp_f32_e32 v76, v76
	v_exp_f32_e32 v77, v77
	v_add_f32_e32 v74, 1.0, v74
	v_add_f32_e32 v75, 1.0, v75
	v_add_f32_e32 v76, 1.0, v76
	v_add_f32_e32 v77, 1.0, v77
	v_rcp_f32_e32 v74, v74
	v_rcp_f32_e32 v75, v75
	v_rcp_f32_e32 v76, v76
	v_rcp_f32_e32 v77, v77
	v_mul_f32_e32 v74, v36, v74
	v_mul_f32_e32 v75, v37, v75
	v_mul_f32_e32 v76, v38, v76
	v_mul_f32_e32 v77, v39, v77
	ds_write_b128 v15, v[74:77] offset:16
	v_mul_f32_e32 v74, 0xbfb8aa3b, v40
	v_mul_f32_e32 v75, 0xbfb8aa3b, v41
	v_mul_f32_e32 v76, 0xbfb8aa3b, v42
	v_mul_f32_e32 v77, 0xbfb8aa3b, v43
	v_exp_f32_e32 v74, v74
	v_exp_f32_e32 v75, v75
	v_exp_f32_e32 v76, v76
	v_exp_f32_e32 v77, v77
	v_add_f32_e32 v74, 1.0, v74
	v_add_f32_e32 v75, 1.0, v75
	v_add_f32_e32 v76, 1.0, v76
	v_add_f32_e32 v77, 1.0, v77
	v_rcp_f32_e32 v74, v74
	v_rcp_f32_e32 v75, v75
	v_rcp_f32_e32 v76, v76
	v_rcp_f32_e32 v77, v77
	v_mul_f32_e32 v74, v40, v74
	v_mul_f32_e32 v75, v41, v75
	v_mul_f32_e32 v76, v42, v76
	v_mul_f32_e32 v77, v43, v77
	ds_write_b128 v15, v[74:77] offset:32784
	v_mul_f32_e32 v74, 0xbfb8aa3b, v44
	v_mul_f32_e32 v75, 0xbfb8aa3b, v45
	v_mul_f32_e32 v76, 0xbfb8aa3b, v46
	v_mul_f32_e32 v77, 0xbfb8aa3b, v47
	v_exp_f32_e32 v74, v74
	v_exp_f32_e32 v75, v75
	v_exp_f32_e32 v76, v76
	v_exp_f32_e32 v77, v77
	v_add_f32_e32 v74, 1.0, v74
	v_add_f32_e32 v75, 1.0, v75
	v_add_f32_e32 v76, 1.0, v76
	v_add_f32_e32 v77, 1.0, v77
	v_rcp_f32_e32 v74, v74
	v_rcp_f32_e32 v75, v75
	v_rcp_f32_e32 v76, v76
	v_rcp_f32_e32 v77, v77
	v_mul_f32_e32 v74, v44, v74
	v_mul_f32_e32 v75, v45, v75
	v_mul_f32_e32 v76, v46, v76
	v_mul_f32_e32 v77, v47, v77
	ds_write_b128 v16, v[74:77] offset:16
	v_mul_f32_e32 v74, 0xbfb8aa3b, v48
	v_mul_f32_e32 v75, 0xbfb8aa3b, v49
	v_mul_f32_e32 v76, 0xbfb8aa3b, v50
	v_mul_f32_e32 v77, 0xbfb8aa3b, v51
	v_exp_f32_e32 v74, v74
	v_exp_f32_e32 v75, v75
	v_exp_f32_e32 v76, v76
	v_exp_f32_e32 v77, v77
	v_add_f32_e32 v74, 1.0, v74
	v_add_f32_e32 v75, 1.0, v75
	v_add_f32_e32 v76, 1.0, v76
	v_add_f32_e32 v77, 1.0, v77
	v_rcp_f32_e32 v74, v74
	v_rcp_f32_e32 v75, v75
	v_rcp_f32_e32 v76, v76
	v_rcp_f32_e32 v77, v77
	v_mul_f32_e32 v74, v48, v74
	v_mul_f32_e32 v75, v49, v75
	v_mul_f32_e32 v76, v50, v76
	v_mul_f32_e32 v77, v51, v77
	ds_write_b128 v16, v[74:77] offset:32784
	v_add_u32_e32 v52, 0x18000, v13
	v_add_u32_e32 v53, 0x19000, v13
	v_add_u32_e32 v54, 0x1a000, v13
	v_add_u32_e32 v55, 0x1b000, v13
	v_add_u32_e32 v56, 0x1c000, v13
	v_add_u32_e32 v57, 0x1d000, v13
	v_add_u32_e32 v58, 0x1e000, v13
	v_add_u32_e32 v59, 0x1f000, v13
	global_load_dword v36, v52, s[6:7]
	global_load_dword v37, v54, s[6:7]
	global_load_dword v38, v56, s[6:7]
	global_load_dword v39, v58, s[6:7]
	global_load_dword v40, v52, s[6:7] offset:2048
	global_load_dword v41, v54, s[6:7] offset:2048
	global_load_dword v42, v56, s[6:7] offset:2048
	global_load_dword v43, v58, s[6:7] offset:2048
	global_load_dword v44, v53, s[6:7]
	global_load_dword v45, v55, s[6:7]
	global_load_dword v46, v57, s[6:7]
	global_load_dword v47, v59, s[6:7]
	global_load_dword v48, v53, s[6:7] offset:2048
	global_load_dword v49, v55, s[6:7] offset:2048
	global_load_dword v50, v57, s[6:7] offset:2048
	global_load_dword v51, v59, s[6:7] offset:2048
	s_waitcnt vmcnt(16)
	v_mul_f32_e32 v74, 0xbfb8aa3b, v20
	v_mul_f32_e32 v75, 0xbfb8aa3b, v21
	v_mul_f32_e32 v76, 0xbfb8aa3b, v22
	v_mul_f32_e32 v77, 0xbfb8aa3b, v23
	v_exp_f32_e32 v74, v74
	v_exp_f32_e32 v75, v75
	v_exp_f32_e32 v76, v76
	v_exp_f32_e32 v77, v77
	v_add_f32_e32 v74, 1.0, v74
	v_add_f32_e32 v75, 1.0, v75
	v_add_f32_e32 v76, 1.0, v76
	v_add_f32_e32 v77, 1.0, v77
	v_rcp_f32_e32 v74, v74
	v_rcp_f32_e32 v75, v75
	v_rcp_f32_e32 v76, v76
	v_rcp_f32_e32 v77, v77
	v_mul_f32_e32 v74, v20, v74
	v_mul_f32_e32 v75, v21, v75
	v_mul_f32_e32 v76, v22, v76
	v_mul_f32_e32 v77, v23, v77
	ds_write_b128 v15, v[74:77] offset:32
	v_mul_f32_e32 v74, 0xbfb8aa3b, v24
	v_mul_f32_e32 v75, 0xbfb8aa3b, v25
	v_mul_f32_e32 v76, 0xbfb8aa3b, v26
	v_mul_f32_e32 v77, 0xbfb8aa3b, v27
	v_exp_f32_e32 v74, v74
	v_exp_f32_e32 v75, v75
	v_exp_f32_e32 v76, v76
	v_exp_f32_e32 v77, v77
	v_add_f32_e32 v74, 1.0, v74
	v_add_f32_e32 v75, 1.0, v75
	v_add_f32_e32 v76, 1.0, v76
	v_add_f32_e32 v77, 1.0, v77
	v_rcp_f32_e32 v74, v74
	v_rcp_f32_e32 v75, v75
	v_rcp_f32_e32 v76, v76
	v_rcp_f32_e32 v77, v77
	v_mul_f32_e32 v74, v24, v74
	v_mul_f32_e32 v75, v25, v75
	v_mul_f32_e32 v76, v26, v76
	v_mul_f32_e32 v77, v27, v77
	ds_write_b128 v15, v[74:77] offset:32800
	v_mul_f32_e32 v74, 0xbfb8aa3b, v28
	v_mul_f32_e32 v75, 0xbfb8aa3b, v29
	v_mul_f32_e32 v76, 0xbfb8aa3b, v30
	v_mul_f32_e32 v77, 0xbfb8aa3b, v31
	v_exp_f32_e32 v74, v74
	v_exp_f32_e32 v75, v75
	v_exp_f32_e32 v76, v76
	v_exp_f32_e32 v77, v77
	v_add_f32_e32 v74, 1.0, v74
	v_add_f32_e32 v75, 1.0, v75
	v_add_f32_e32 v76, 1.0, v76
	v_add_f32_e32 v77, 1.0, v77
	v_rcp_f32_e32 v74, v74
	v_rcp_f32_e32 v75, v75
	v_rcp_f32_e32 v76, v76
	v_rcp_f32_e32 v77, v77
	v_mul_f32_e32 v74, v28, v74
	v_mul_f32_e32 v75, v29, v75
	v_mul_f32_e32 v76, v30, v76
	v_mul_f32_e32 v77, v31, v77
	ds_write_b128 v16, v[74:77] offset:32
	v_mul_f32_e32 v74, 0xbfb8aa3b, v32
	v_mul_f32_e32 v75, 0xbfb8aa3b, v33
	v_mul_f32_e32 v76, 0xbfb8aa3b, v34
	v_mul_f32_e32 v77, 0xbfb8aa3b, v35
	v_exp_f32_e32 v74, v74
	v_exp_f32_e32 v75, v75
	v_exp_f32_e32 v76, v76
	v_exp_f32_e32 v77, v77
	v_add_f32_e32 v74, 1.0, v74
	v_add_f32_e32 v75, 1.0, v75
	v_add_f32_e32 v76, 1.0, v76
	v_add_f32_e32 v77, 1.0, v77
	v_rcp_f32_e32 v74, v74
	v_rcp_f32_e32 v75, v75
	v_rcp_f32_e32 v76, v76
	v_rcp_f32_e32 v77, v77
	v_mul_f32_e32 v74, v32, v74
	v_mul_f32_e32 v75, v33, v75
	v_mul_f32_e32 v76, v34, v76
	v_mul_f32_e32 v77, v35, v77
	ds_write_b128 v16, v[74:77] offset:32800
	s_waitcnt vmcnt(0)
	v_mul_f32_e32 v74, 0xbfb8aa3b, v36
	v_mul_f32_e32 v75, 0xbfb8aa3b, v37
	v_mul_f32_e32 v76, 0xbfb8aa3b, v38
	v_mul_f32_e32 v77, 0xbfb8aa3b, v39
	v_exp_f32_e32 v74, v74
	v_exp_f32_e32 v75, v75
	v_exp_f32_e32 v76, v76
	v_exp_f32_e32 v77, v77
	v_add_f32_e32 v74, 1.0, v74
	v_add_f32_e32 v75, 1.0, v75
	v_add_f32_e32 v76, 1.0, v76
	v_add_f32_e32 v77, 1.0, v77
	v_rcp_f32_e32 v74, v74
	v_rcp_f32_e32 v75, v75
	v_rcp_f32_e32 v76, v76
	v_rcp_f32_e32 v77, v77
	v_mul_f32_e32 v74, v36, v74
	v_mul_f32_e32 v75, v37, v75
	v_mul_f32_e32 v76, v38, v76
	v_mul_f32_e32 v77, v39, v77
	ds_write_b128 v15, v[74:77] offset:48
	v_mul_f32_e32 v74, 0xbfb8aa3b, v40
	v_mul_f32_e32 v75, 0xbfb8aa3b, v41
	v_mul_f32_e32 v76, 0xbfb8aa3b, v42
	v_mul_f32_e32 v77, 0xbfb8aa3b, v43
	v_exp_f32_e32 v74, v74
	v_exp_f32_e32 v75, v75
	v_exp_f32_e32 v76, v76
	v_exp_f32_e32 v77, v77
	v_add_f32_e32 v74, 1.0, v74
	v_add_f32_e32 v75, 1.0, v75
	v_add_f32_e32 v76, 1.0, v76
	v_add_f32_e32 v77, 1.0, v77
	v_rcp_f32_e32 v74, v74
	v_rcp_f32_e32 v75, v75
	v_rcp_f32_e32 v76, v76
	v_rcp_f32_e32 v77, v77
	v_mul_f32_e32 v74, v40, v74
	v_mul_f32_e32 v75, v41, v75
	v_mul_f32_e32 v76, v42, v76
	v_mul_f32_e32 v77, v43, v77
	ds_write_b128 v15, v[74:77] offset:32816
	v_mul_f32_e32 v74, 0xbfb8aa3b, v44
	v_mul_f32_e32 v75, 0xbfb8aa3b, v45
	v_mul_f32_e32 v76, 0xbfb8aa3b, v46
	v_mul_f32_e32 v77, 0xbfb8aa3b, v47
	v_exp_f32_e32 v74, v74
	v_exp_f32_e32 v75, v75
	v_exp_f32_e32 v76, v76
	v_exp_f32_e32 v77, v77
	v_add_f32_e32 v74, 1.0, v74
	v_add_f32_e32 v75, 1.0, v75
	v_add_f32_e32 v76, 1.0, v76
	v_add_f32_e32 v77, 1.0, v77
	v_rcp_f32_e32 v74, v74
	v_rcp_f32_e32 v75, v75
	v_rcp_f32_e32 v76, v76
	v_rcp_f32_e32 v77, v77
	v_mul_f32_e32 v74, v44, v74
	v_mul_f32_e32 v75, v45, v75
	v_mul_f32_e32 v76, v46, v76
	v_mul_f32_e32 v77, v47, v77
	ds_write_b128 v16, v[74:77] offset:48
	v_mul_f32_e32 v74, 0xbfb8aa3b, v48
	v_mul_f32_e32 v75, 0xbfb8aa3b, v49
	v_mul_f32_e32 v76, 0xbfb8aa3b, v50
	v_mul_f32_e32 v77, 0xbfb8aa3b, v51
	v_exp_f32_e32 v74, v74
	v_exp_f32_e32 v75, v75
	v_exp_f32_e32 v76, v76
	v_exp_f32_e32 v77, v77
	v_add_f32_e32 v74, 1.0, v74
	v_add_f32_e32 v75, 1.0, v75
	v_add_f32_e32 v76, 1.0, v76
	v_add_f32_e32 v77, 1.0, v77
	v_rcp_f32_e32 v74, v74
	v_rcp_f32_e32 v75, v75
	v_rcp_f32_e32 v76, v76
	v_rcp_f32_e32 v77, v77
	v_mul_f32_e32 v74, v48, v74
	v_mul_f32_e32 v75, v49, v75
	v_mul_f32_e32 v76, v50, v76
	v_mul_f32_e32 v77, v51, v77
	ds_write_b128 v16, v[74:77] offset:32816
